# phase-0 grid sync routed through the XCD-hierarchical barrier instead of cooperative-groups sync
# baseline (speedup 1.0000x reference)
; #define LAS __attribute__((address_space(3)))
; __device__ __forceinline__ unsigned xb_ld(unsigned* p)              { return __hip_atomic_load(p, __ATOMIC_RELAXED, __HIP_MEMORY_SCOPE_AGENT); }
; __device__ __forceinline__ void xcd_barrier_complete(unsigned* bar, unsigned x, unsigned& nloc, unsigned& nx) {
;     const unsigned G = gridDim.x * gridDim.y * gridDim.z;
;     unsigned sum, cnt, mine, sp = 0u;
;     for (;;) {
;         sum = 0u; cnt = 0u; mine = 0u;
; #pragma unroll
;         for (unsigned j = 0; j < 16; ++j) { const unsigned c = xb_ld(&bar[XB_XCNT(j)]); sum += c; cnt += (c > 0u) ? 1u : 0u; mine = (j == x) ? c : mine; }
; __device__ __forceinline__ void xcd_barrier(unsigned* bar, unsigned x, volatile LAS unsigned* st) {
;     asm volatile("s_waitcnt vmcnt(0)" ::: "memory");
;     __syncthreads();
;     if (threadIdx.x == 0) {
;         __builtin_amdgcn_s_waitcnt(0);
;         unsigned nloc = st[0], nx = st[1];
;         if (nloc == 0u) { xcd_barrier_complete(bar, x, nloc, nx); st[0] = nloc; st[1] = nx; }
.LBB0_903:
	v_readlane_b32 s4, v255, 4
	v_readlane_b32 s5, v255, 5
	s_mov_b64 s[0:1], -1
	s_and_b64 vcc, exec, s[4:5]
	s_waitcnt vmcnt(0)
	s_waitcnt vmcnt(0) lgkmcnt(0)
	s_barrier
	s_mov_b64 s[0:1], exec
	v_readlane_b32 s4, v254, 46
	v_readlane_b32 s5, v254, 47
	s_and_b64 s[4:5], s[0:1], s[4:5]
	s_mov_b64 exec, s[4:5]
	s_cbranch_execz .LBB0_967
	v_readlane_b32 s4, v254, 44
	s_waitcnt vmcnt(0) expcnt(0) lgkmcnt(0)
	s_nop 0
	v_mov_b32_e32 v0, s4
	ds_read_b32 v2, v0
	v_readlane_b32 s4, v254, 45
	s_waitcnt lgkmcnt(0)
	v_cmp_ne_u32_e32 vcc, 0, v2
	v_mov_b32_e32 v0, s4
	ds_read_b32 v0, v0
	s_cbranch_vccnz .LBB0_920
	s_load_dwordx2 s[8:9], s[86:87], 0x0
	s_load_dword s7, s[86:87], 0x8
	s_add_u32 s4, s94, 0x3ff00200
	s_addc_u32 s5, s95, 0
	s_add_u32 s6, s94, 0x3ff00400
	s_waitcnt lgkmcnt(0)
	s_mul_i32 s46, s9, s8
	s_mul_i32 s46, s46, s7
	s_addc_u32 s7, s95, 0
	s_add_u32 s8, s94, 0x3ff00500
	s_addc_u32 s9, s95, 0
	s_add_u32 s10, s94, 0x3ff00600
	s_addc_u32 s11, s95, 0
	s_add_u32 s12, s94, 0x3ff00700
	s_addc_u32 s13, s95, 0
	s_add_u32 s14, s94, 0x3ff00800
	s_addc_u32 s15, s95, 0
	s_add_u32 s16, s94, 0x3ff00900
	s_addc_u32 s17, s95, 0
	s_add_u32 s18, s94, 0x3ff00a00
	s_addc_u32 s19, s95, 0
	s_add_u32 s20, s94, 0x3ff00b00
	s_addc_u32 s21, s95, 0
	s_add_u32 s22, s94, 0x3ff00c00
	s_addc_u32 s23, s95, 0
	s_add_u32 s24, s94, 0x3ff00d00
	s_addc_u32 s25, s95, 0
	s_add_u32 s26, s94, 0x3ff00e00
	s_addc_u32 s27, s95, 0
	s_add_u32 s28, s94, 0x3ff00f00
	s_addc_u32 s29, s95, 0
	s_add_u32 s30, s94, 0x3ff01000
	s_addc_u32 s31, s95, 0
	s_add_u32 s34, s94, 0x3ff01100
	s_addc_u32 s35, s95, 0
	s_add_u32 s36, s94, 0x3ff01200
	s_addc_u32 s37, s95, 0
	s_add_u32 s38, s94, 0x3ff01300
	s_addc_u32 s39, s95, 0
	s_mov_b32 s47, 1
	s_branch .LBB0_908
